# MLA: next tile's head (index, flags, LDS read addresses, first-block test) computed in front of the tile-end barrier
# baseline (speedup 1.0000x reference)
; template <int DQK, int DV, bool CAUSAL, int KT, bool PRIO>
; DI void attn_unit(const bf16_t* Qb, int qpitch, const bf16_t* Kb, int kpitch, const bf16_t* Vtb, int vpitch, bf16_t* Ob, int opitch, int q0, int nt, LAS unsigned char* lds, float kbound, const float* qgain, const int* qpos, float qscale) {
;     ...
;     auto gload = [&](int kt) {
; #pragma unroll
;         for (int i = 0; i < NKR; ++i) { const int c = tid + i * 512; if (NKC % 512 == 0 || c < NKC) kreg[i] = *(const u32x4*)(Kb + (size_t)(kt * KT + c / KCH) * kpitch + (c % KCH) * 8); }
; #pragma unroll
;         for (int i = 0; i < NVR; ++i) { const int c = tid + i * 512; vreg[i] = *(const u32x4*)(Vtb + (size_t)(c / VCH) * vpitch + kt * KT + (c % VCH) * 8); }
;     };
;     ...
;         if (kt + 1 < nt) gload(kt + 1);
; #pragma unroll
;         for (int hf = 0; hf < KT / 64; ++hf) {
;             const int key0 = kt * KT + 64 * hf;
;             if (!CAUSAL || key0 <= qlo + 31) {
.Lmla_1490:
	global_load_dwordx4 v[96:99], v[172:173], off
	global_load_dwordx4 v[100:103], v[170:171], off
	global_load_dwordx4 v[104:107], v[168:169], off
	global_load_dwordx4 v[108:111], v[166:167], off
	global_load_dwordx4 v[112:115], v[164:165], off
	v_lshl_add_u64 v[164:165], v[164:165], 0, s[14:15]
	v_lshl_add_u64 v[166:167], v[166:167], 0, s[14:15]
	v_lshl_add_u64 v[168:169], v[168:169], 0, s[16:17]
	v_lshl_add_u64 v[170:171], v[170:171], 0, s[16:17]
	v_lshl_add_u64 v[172:173], v[172:173], 0, s[16:17]
	s_add_i32 s12, s71, 1
	s_cmp_gt_i32 s12, s70
	s_cbranch_scc0 .Lmla_b1_pre

; #define LAS __attribute__((address_space(3)))
; template <int DQK, int DV, bool CAUSAL, int KT, bool PRIO>
; DI void attn_unit(const bf16_t* Qb, int qpitch, const bf16_t* Kb, int kpitch, const bf16_t* Vtb, int vpitch, bf16_t* Ob, int opitch, int q0, int nt, LAS unsigned char* lds, float kbound, const float* qgain, const int* qpos, float qscale) {
;     ...
;     for (int kt = 0; kt < nt; ++kt) {
;         const int buf = kt & 1;
;         if (kt + 1 < nt) gload(kt + 1);
; #pragma unroll
;         for (int hf = 0; hf < KT / 64; ++hf) {
;             const int key0 = kt * KT + 64 * hf;
;             if (!CAUSAL || key0 <= qlo + 31) {
;                 if (PRIO) {
;                     constexpr int KSN = DQK / 16, NDB = DV / 32;
;                     f32x16 s0 = negm, s1 = negm;
;                     const LAS unsigned char* kb = lds + buf * KBUF + (64 * hf + r) * KS + h * 16;
;                     const LAS unsigned char* vb = lds + VOFF + buf * VBUF + r * VS + h * 8 + 128 * hf;
;     ...
;         if (kt + 1 < nt) lstore(buf ^ 1);
;         __syncthreads();
;     }
.LBB0_1493:
	s_addk_i32 s71, 0x80
	s_cmp_lg_u32 s68, s74
	s_cbranch_scc0 .Lmla_lastt
	s_mov_b32 s12, s74
	s_add_i32 s74, s12, 1
	s_cmp_lt_u32 s74, s68
	s_cselect_b64 s[38:39], -1, 0
	s_and_b32 s75, s12, 1
	s_mul_i32 s13, s75, 0x6800
	v_add_u32_e32 v2, s13, v190
	s_mul_i32 s13, s75, 0x4400
	s_sub_i32 s12, s71, 63
	v_add_u32_e32 v194, v2, v192
	v_add_u32_e32 v2, s13, v191
	v_add_u32_e32 v14, 0xd000, v2
	v_add_u32_e32 v15, 0xf200, v2
	s_cmp_gt_i32 s12, s70
	s_waitcnt lgkmcnt(0)
	s_barrier
	s_cbranch_scc0 .LBB0_1495
	s_branch .Lmla_1490
.Lmla_lastt:
	s_waitcnt lgkmcnt(0)
	s_barrier
	s_branch .LBB0_1479
	s_nop 0
	s_nop 0
	s_nop 0
